# v83 + hot loop headers (9 GEMM K-loops, scan chunk loops, attention tile loop) aligned to 64-byte instruction-cache lines
# speedup vs baseline: 1.0045x; 1.0045x over previous
.LBB0_225:
	s_ashr_i32 s17, s16, 31
	s_lshl_b64 s[18:19], s[16:17], 20
	s_add_u32 s18, s30, s18
	s_addc_u32 s19, s31, s19
	s_and_b64 s[20:21], s[4:5], exec
	s_cselect_b32 s17, s19, s25
	s_cselect_b32 s54, s18, s24
	s_ashr_i32 s15, s14, 31
	s_lshl_b64 s[20:21], s[14:15], 20
	s_add_u32 s20, s34, s20
	s_addc_u32 s21, s35, s21
	s_and_b64 s[28:29], s[4:5], exec
	s_cselect_b32 s15, s21, s27
	s_cselect_b32 s55, s20, s26
	s_add_u32 s24, s24, 0x80080
	s_addc_u32 s25, s25, 0
	s_add_u32 s58, s26, 0x100
	v_mov_b32_e32 v0, 0
	s_addc_u32 s59, s27, 0
	s_mov_b32 s60, -2
	v_mov_b32_e32 v1, v0
	v_mov_b32_e32 v2, v0
	v_mov_b32_e32 v3, v0
	v_mov_b32_e32 v4, v0
	v_mov_b32_e32 v5, v0
	v_mov_b32_e32 v6, v0
	v_mov_b32_e32 v7, v0
	v_mov_b32_e32 v8, v0
	v_mov_b32_e32 v9, v0
	v_mov_b32_e32 v10, v0
	v_mov_b32_e32 v11, v0
	v_mov_b32_e32 v16, v0
	v_mov_b32_e32 v17, v0
	v_mov_b32_e32 v18, v0
	v_mov_b32_e32 v19, v0
	v_mov_b32_e32 v24, v0
	v_mov_b32_e32 v25, v0
	v_mov_b32_e32 v26, v0
	v_mov_b32_e32 v27, v0
	v_mov_b32_e32 v32, v0
	v_mov_b32_e32 v33, v0
	v_mov_b32_e32 v34, v0
	v_mov_b32_e32 v35, v0
	v_mov_b32_e32 v40, v0
	v_mov_b32_e32 v41, v0
	v_mov_b32_e32 v42, v0
	v_mov_b32_e32 v43, v0
	v_mov_b32_e32 v48, v0
	v_mov_b32_e32 v49, v0
	v_mov_b32_e32 v50, v0
	v_mov_b32_e32 v51, v0
	v_mov_b32_e32 v12, v0
	v_mov_b32_e32 v13, v0
	v_mov_b32_e32 v14, v0
	v_mov_b32_e32 v15, v0
	v_mov_b32_e32 v20, v0
	v_mov_b32_e32 v21, v0
	v_mov_b32_e32 v22, v0
	v_mov_b32_e32 v23, v0
	v_mov_b32_e32 v28, v0
	v_mov_b32_e32 v29, v0
	v_mov_b32_e32 v30, v0
	v_mov_b32_e32 v31, v0
	v_mov_b32_e32 v36, v0
	v_mov_b32_e32 v37, v0
	v_mov_b32_e32 v38, v0
	v_mov_b32_e32 v39, v0
	v_mov_b32_e32 v44, v0
	v_mov_b32_e32 v45, v0
	v_mov_b32_e32 v46, v0
	v_mov_b32_e32 v47, v0
	v_mov_b32_e32 v52, v0
	v_mov_b32_e32 v53, v0
	v_mov_b32_e32 v54, v0
	v_mov_b32_e32 v55, v0
	v_mov_b32_e32 v56, v0
	v_mov_b32_e32 v57, v0
	v_mov_b32_e32 v58, v0
	v_mov_b32_e32 v59, v0
	v_mov_b32_e32 v60, v0
	v_mov_b32_e32 v61, v0
	v_mov_b32_e32 v62, v0
	v_mov_b32_e32 v63, v0
	v_mov_b32_e32 v64, v0
	v_mov_b32_e32 v65, v0
	v_mov_b32_e32 v66, v0
	v_mov_b32_e32 v67, v0
	v_mov_b32_e32 v68, v0
	v_mov_b32_e32 v69, v0
	v_mov_b32_e32 v70, v0
	v_mov_b32_e32 v71, v0
	v_mov_b32_e32 v72, v0
	v_mov_b32_e32 v73, v0
	v_mov_b32_e32 v74, v0
	v_mov_b32_e32 v75, v0
	v_mov_b32_e32 v80, v0
	v_mov_b32_e32 v81, v0
	v_mov_b32_e32 v82, v0
	v_mov_b32_e32 v83, v0
	v_mov_b32_e32 v88, v0
	v_mov_b32_e32 v89, v0
	v_mov_b32_e32 v90, v0
	v_mov_b32_e32 v91, v0
	v_mov_b32_e32 v96, v0
	v_mov_b32_e32 v97, v0
	v_mov_b32_e32 v98, v0
	v_mov_b32_e32 v99, v0
	v_mov_b32_e32 v104, v0
	v_mov_b32_e32 v105, v0
	v_mov_b32_e32 v106, v0
	v_mov_b32_e32 v107, v0
	v_mov_b32_e32 v112, v0
	v_mov_b32_e32 v113, v0
	v_mov_b32_e32 v114, v0
	v_mov_b32_e32 v115, v0
	v_mov_b32_e32 v76, v0
	v_mov_b32_e32 v77, v0
	v_mov_b32_e32 v78, v0
	v_mov_b32_e32 v79, v0
	v_mov_b32_e32 v84, v0
	v_mov_b32_e32 v85, v0
	v_mov_b32_e32 v86, v0
	v_mov_b32_e32 v87, v0
	v_mov_b32_e32 v92, v0
	v_mov_b32_e32 v93, v0
	v_mov_b32_e32 v94, v0
	v_mov_b32_e32 v95, v0
	v_mov_b32_e32 v100, v0
	v_mov_b32_e32 v101, v0
	v_mov_b32_e32 v102, v0
	v_mov_b32_e32 v103, v0
	v_mov_b32_e32 v108, v0
	v_mov_b32_e32 v109, v0
	v_mov_b32_e32 v110, v0
	v_mov_b32_e32 v111, v0
	v_mov_b32_e32 v116, v0
	v_mov_b32_e32 v117, v0
	v_mov_b32_e32 v118, v0
	v_mov_b32_e32 v119, v0
	v_mov_b32_e32 v120, v0
	v_mov_b32_e32 v121, v0
	v_mov_b32_e32 v122, v0
	v_mov_b32_e32 v123, v0
	v_mov_b32_e32 v124, v0
	v_mov_b32_e32 v125, v0
	v_mov_b32_e32 v126, v0
	v_mov_b32_e32 v127, v0
	.p2alignl 6, 3212836864

.LBB0_455:
	s_lshl_b32 s54, s73, 1
	s_and_b32 s95, s54, 0xc00
	s_and_b32 s54, s75, -16
	s_lshl_b32 s33, s90, 22
	s_ashr_i32 s55, s54, 31
	s_and_b32 s18, s90, 7
	s_and_b32 s33, s33, 0x1000000
	s_lshl_b64 s[60:61], s[54:55], 1
	s_add_u32 s54, s60, s95
	s_addc_u32 s55, s61, 0
	s_add_u32 s54, s54, s33
	s_addc_u32 s55, s55, 0
	s_and_b32 s93, s91, 7
	v_lshl_add_u64 v[164:165], s[54:55], 0, v[150:151]
	s_lshl_b32 s62, s18, 21
	s_mov_b32 s63, s19
	s_lshl_b32 s64, s18, 16
	s_mov_b32 s65, s19
	s_lshl_b32 s92, s93, 6
	s_lshl_b32 s94, s93, 20
	s_mov_b64 s[66:67], -1
	s_and_b64 vcc, exec, s[16:17]
	s_cbranch_vccz .LBB0_459
	s_mov_b64 s[54:55], s[0:1]
	s_load_dwordx2 s[66:67], s[54:55], 0x80
	s_lshl_b32 s18, s18, 19
	v_lshl_add_u64 v[170:171], v[156:157], 0, s[18:19]
	s_lshl_b32 s18, s94, 1
	v_mov_b32_e32 v132, 0
	s_waitcnt lgkmcnt(0)
	s_add_u32 s18, s66, s18
	s_addc_u32 s33, s67, 0
	s_add_u32 s54, s18, s20
	s_addc_u32 s55, s33, s21
	s_lshl_b32 s18, s92, 13
	s_add_u32 s18, s66, s18
	s_addc_u32 s33, s67, 0
	s_add_u32 s96, s18, s24
	s_addc_u32 s97, s33, s25
	s_lshl_b32 s18, s92, 10
	s_add_u32 s18, s66, s18
	s_addc_u32 s33, s67, 0
	s_add_u32 s56, s18, s22
	v_lshl_add_u64 v[24:25], s[96:97], 0, v[140:141]
	s_mov_b32 s18, 0x15700000
	v_add_co_u32_e32 v0, vcc, s18, v24
	v_lshl_add_u64 v[26:27], s[54:55], 0, v[140:141]
	s_nop 0
	v_addc_co_u32_e32 v1, vcc, 0, v25, vcc
	v_add_co_u32_e32 v4, vcc, s78, v26
	s_addc_u32 s57, s33, s23
	s_nop 0
	v_addc_co_u32_e32 v5, vcc, 0, v27, vcc
	global_load_dwordx4 v[0:3], v[0:1], off
	v_lshl_add_u64 v[174:175], v[26:27], 0, s[30:31]
	global_load_dwordx4 v[44:47], v[4:5], off
	global_load_dwordx4 v[52:55], v[174:175], off offset:1024
	global_load_dwordx4 v[28:31], v[174:175], off offset:2048
	global_load_dwordx4 v[20:23], v[174:175], off offset:3072
	v_add_co_u32_e32 v4, vcc, s79, v26
	s_waitcnt vmcnt(9)
	v_lshl_add_u64 v[32:33], s[56:57], 0, v[144:145]
	v_addc_co_u32_e32 v5, vcc, 0, v27, vcc
	v_lshl_add_u64 v[178:179], v[32:33], 0, s[36:37]
	v_add_co_u32_e32 v32, vcc, s80, v32
	s_mov_b64 s[96:97], 0x15700000
	s_nop 0
	v_addc_co_u32_e32 v33, vcc, 0, v33, vcc
	s_mov_b32 s18, 0x15702000
	v_lshl_add_u64 v[172:173], v[24:25], 0, s[96:97]
	v_add_co_u32_e32 v24, vcc, s18, v24
	v_lshl_add_u64 v[176:177], v[26:27], 0, s[34:35]
	s_nop 0
	v_addc_co_u32_e32 v25, vcc, 0, v25, vcc
	global_load_dwordx4 v[16:19], v[4:5], off
	global_load_dwordx4 v[12:15], v[176:177], off offset:1024
	s_nop 0
	global_load_dwordx4 v[4:7], v[176:177], off offset:2048
	global_load_dwordx4 v[8:11], v[176:177], off offset:3072
	global_load_dwordx4 v[40:43], v[32:33], off
	global_load_dwordx4 v[36:39], v[178:179], off offset:64
	v_add_co_u32_e32 v32, vcc, s81, v26
	global_load_dwordx4 v[60:63], v[24:25], off
	v_lshl_add_u64 v[24:25], v[26:27], 0, s[38:39]
	v_addc_co_u32_e32 v33, vcc, 0, v27, vcc
	global_load_dwordx4 v[72:75], v[32:33], off
	global_load_dwordx4 v[76:79], v[24:25], off offset:1024
	global_load_dwordx4 v[80:83], v[24:25], off offset:2048
	global_load_dwordx4 v[84:87], v[24:25], off offset:3072
	v_add_co_u32_e32 v24, vcc, 0x16708000, v26
	v_lshl_add_u64 v[32:33], v[26:27], 0, s[40:41]
	s_nop 0
	v_addc_co_u32_e32 v25, vcc, 0, v27, vcc
	global_load_dwordx4 v[56:59], v[24:25], off
	global_load_dwordx4 v[48:51], v[32:33], off offset:1024
	s_nop 0
	global_load_dwordx4 v[24:27], v[32:33], off offset:2048
	s_nop 0
	global_load_dwordx4 v[32:35], v[32:33], off offset:3072
	s_nop 0
	global_load_dwordx4 v[64:67], v[178:179], off offset:1024
	global_load_dwordx4 v[68:71], v[178:179], off offset:1088
	v_lshl_add_u64 v[166:167], v[152:153], 0, s[62:63]
	v_lshl_add_u64 v[168:169], v[154:155], 0, s[64:65]
	s_mov_b32 s18, -3
	v_mov_b64_e32 v[180:181], v[164:165]
	v_mov_b32_e32 v133, v132
	v_mov_b32_e32 v134, v132
	v_mov_b32_e32 v135, v132
	v_mov_b32_e32 v136, v132
	v_mov_b32_e32 v137, v132
	v_mov_b32_e32 v138, v132
	v_mov_b32_e32 v139, v132
	s_barrier
	.p2alignl 6, 3212836864

.LBB0_459:
	s_and_b64 vcc, exec, s[66:67]
	s_cbranch_vccz .LBB0_454
	s_lshl_b32 s18, s90, 10
	s_and_b32 s18, s18, 0x1000
	v_add_u32_e32 v0, s18, v199
	v_mad_u64_u32 v[0:1], s[54:55], v0, s89, 0
	s_add_u32 s54, s60, s95
	v_or_b32_e32 v0, v162, v0
	s_addc_u32 s55, s61, 0
	v_lshl_add_u64 v[170:171], s[54:55], 0, v[0:1]
	s_mov_b64 s[54:55], s[0:1]
	s_load_dwordx2 s[60:61], s[54:55], 0x80
	s_lshl_b32 s18, s94, 1
	v_lshl_add_u64 v[168:169], v[160:161], 0, s[64:65]
	v_lshl_add_u64 v[166:167], v[158:159], 0, s[62:63]
	s_mov_b64 s[66:67], 0xe601000
	s_waitcnt lgkmcnt(0)
	s_add_u32 s18, s60, s18
	s_addc_u32 s33, s61, 0
	s_add_u32 s54, s18, s26
	s_addc_u32 s55, s33, s27
	s_lshl_b32 s18, s93, 10
	s_and_b32 s64, s18, 0x1000
	s_lshl_b32 s18, s91, 9
	v_add_u32_e32 v2, s64, v198
	v_mov_b64_e32 v[0:1], s[60:61]
	s_and_b32 s65, s18, 0x600
	v_mad_u64_u32 v[0:1], s[62:63], v2, s89, v[0:1]
	s_lshl_b32 s18, s65, 1
	v_lshl_add_u64 v[0:1], v[0:1], 0, s[18:19]
	s_lshl_b32 s18, s91, 1
	s_and_b32 s62, s18, -16
	s_ashr_i32 s63, s62, 31
	s_lshl_b32 s18, s92, 10
	v_lshl_add_u64 v[0:1], s[62:63], 1, v[0:1]
	s_add_u32 s18, s60, s18
	s_waitcnt vmcnt(8)
	v_lshl_add_u64 v[36:37], v[0:1], 0, v[142:143]
	s_addc_u32 s33, s61, 0
	v_lshl_add_u64 v[172:173], v[36:37], 0, s[66:67]
	s_add_u32 s66, s18, s28
	s_mov_b32 s18, 0xe601000
	v_add_co_u32_e32 v0, vcc, s18, v36
	s_waitcnt vmcnt(7)
	v_lshl_add_u64 v[44:45], s[54:55], 0, v[140:141]
	v_addc_co_u32_e32 v1, vcc, 0, v37, vcc
	global_load_dwordx4 v[84:87], v[0:1], off
	v_add_co_u32_e32 v0, vcc, s78, v44
	s_addc_u32 s67, s33, s29
	s_nop 0
	v_addc_co_u32_e32 v1, vcc, 0, v45, vcc
	v_add_co_u32_e32 v16, vcc, s79, v44
	s_waitcnt vmcnt(5)
	v_lshl_add_u64 v[32:33], s[66:67], 0, v[144:145]
	v_addc_co_u32_e32 v17, vcc, 0, v45, vcc
	v_lshl_add_u64 v[178:179], v[32:33], 0, s[36:37]
	v_add_co_u32_e32 v32, vcc, s80, v32
	s_mov_b32 s18, 0xe6c1000
	s_nop 0
	v_addc_co_u32_e32 v33, vcc, 0, v33, vcc
	v_add_co_u32_e32 v36, vcc, s18, v36
	s_mov_b32 s18, 0x16708000
	s_nop 0
	v_addc_co_u32_e32 v37, vcc, 0, v37, vcc
	v_add_co_u32_e32 v38, vcc, s81, v44
	v_lshl_add_u64 v[174:175], v[44:45], 0, s[30:31]
	s_nop 0
	v_addc_co_u32_e32 v39, vcc, 0, v45, vcc
	global_load_dwordx4 v[12:15], v[0:1], off
	global_load_dwordx4 v[8:11], v[174:175], off offset:1024
	global_load_dwordx4 v[4:7], v[174:175], off offset:2048
	s_nop 0
	global_load_dwordx4 v[0:3], v[174:175], off offset:3072
	v_lshl_add_u64 v[176:177], v[44:45], 0, s[34:35]
	global_load_dwordx4 v[24:27], v[16:17], off
	global_load_dwordx4 v[28:31], v[176:177], off offset:1024
	global_load_dwordx4 v[20:23], v[176:177], off offset:2048
	s_nop 0
	global_load_dwordx4 v[16:19], v[176:177], off offset:3072
	global_load_dwordx4 v[40:43], v[32:33], off
	s_nop 0
	global_load_dwordx4 v[32:35], v[178:179], off offset:64
	global_load_dwordx4 v[80:83], v[36:37], off
	v_lshl_add_u64 v[36:37], v[44:45], 0, s[38:39]
	v_lshl_add_u64 v[52:53], v[44:45], 0, s[40:41]
	v_add_co_u32_e32 v44, vcc, s18, v44
	global_load_dwordx4 v[64:67], v[38:39], off
	global_load_dwordx4 v[68:71], v[36:37], off offset:1024
	global_load_dwordx4 v[56:59], v[36:37], off offset:2048
	s_nop 0
	global_load_dwordx4 v[36:39], v[36:37], off offset:3072
	v_addc_co_u32_e32 v45, vcc, 0, v45, vcc
	global_load_dwordx4 v[44:47], v[44:45], off
	s_nop 0
	global_load_dwordx4 v[60:63], v[52:53], off offset:1024
	global_load_dwordx4 v[48:51], v[52:53], off offset:2048
	s_nop 0
	global_load_dwordx4 v[52:55], v[52:53], off offset:3072
	s_nop 0
	global_load_dwordx4 v[76:79], v[178:179], off offset:1024
	global_load_dwordx4 v[72:75], v[178:179], off offset:1088
	v_mov_b32_e32 v128, 0
	v_add_u32_e32 v88, s70, v140
	s_mov_b32 s18, -3
	s_movk_i32 s66, 0x800
	v_mov_b32_e32 v129, v128
	v_mov_b32_e32 v130, v128
	v_mov_b32_e32 v131, v128
	v_mov_b32_e32 v132, v128
	v_mov_b32_e32 v133, v128
	v_mov_b32_e32 v134, v128
	v_mov_b32_e32 v135, v128
	s_waitcnt vmcnt(21)
	ds_write_b128 v88, v[84:87]
	s_waitcnt lgkmcnt(0)
	s_barrier
	.p2alignl 6, 3212836864

.LBB0_588:
	s_ashr_i32 s35, s34, 31
	s_lshl_b64 s[36:37], s[34:35], 20
	s_add_u32 s36, s60, s36
	s_addc_u32 s37, s61, s37
	s_and_b64 s[38:39], s[8:9], exec
	s_cselect_b32 s35, s37, s49
	s_cselect_b32 s41, s36, s48
	s_ashr_i32 s31, s30, 31
	s_lshl_b64 s[38:39], s[30:31], 20
	s_add_u32 s38, s62, s38
	s_addc_u32 s39, s63, s39
	s_and_b64 s[54:55], s[8:9], exec
	s_cselect_b32 s31, s39, s51
	s_cselect_b32 s73, s38, s50
	s_add_u32 s48, s48, 0x80080
	s_addc_u32 s49, s49, 0
	s_add_u32 s74, s50, 0x100
	v_mov_b32_e32 v0, 0
	s_addc_u32 s75, s51, 0
	s_mov_b32 s77, -2
	s_waitcnt lgkmcnt(0)
	v_mov_b32_e32 v1, v0
	v_mov_b32_e32 v2, v0
	v_mov_b32_e32 v3, v0
	v_mov_b32_e32 v4, v0
	v_mov_b32_e32 v5, v0
	v_mov_b32_e32 v6, v0
	v_mov_b32_e32 v7, v0
	v_mov_b32_e32 v16, v0
	v_mov_b32_e32 v17, v0
	v_mov_b32_e32 v18, v0
	v_mov_b32_e32 v19, v0
	v_mov_b32_e32 v20, v0
	v_mov_b32_e32 v21, v0
	v_mov_b32_e32 v22, v0
	v_mov_b32_e32 v23, v0
	v_mov_b32_e32 v32, v0
	v_mov_b32_e32 v33, v0
	v_mov_b32_e32 v34, v0
	v_mov_b32_e32 v35, v0
	v_mov_b32_e32 v36, v0
	v_mov_b32_e32 v37, v0
	v_mov_b32_e32 v38, v0
	v_mov_b32_e32 v39, v0
	v_mov_b32_e32 v48, v0
	v_mov_b32_e32 v49, v0
	v_mov_b32_e32 v50, v0
	v_mov_b32_e32 v51, v0
	v_mov_b32_e32 v52, v0
	v_mov_b32_e32 v53, v0
	v_mov_b32_e32 v54, v0
	v_mov_b32_e32 v55, v0
	v_mov_b32_e32 v8, v0
	v_mov_b32_e32 v9, v0
	v_mov_b32_e32 v10, v0
	v_mov_b32_e32 v11, v0
	v_mov_b32_e32 v12, v0
	v_mov_b32_e32 v13, v0
	v_mov_b32_e32 v14, v0
	v_mov_b32_e32 v15, v0
	v_mov_b32_e32 v24, v0
	v_mov_b32_e32 v25, v0
	v_mov_b32_e32 v26, v0
	v_mov_b32_e32 v27, v0
	v_mov_b32_e32 v28, v0
	v_mov_b32_e32 v29, v0
	v_mov_b32_e32 v30, v0
	v_mov_b32_e32 v31, v0
	v_mov_b32_e32 v40, v0
	v_mov_b32_e32 v41, v0
	v_mov_b32_e32 v42, v0
	v_mov_b32_e32 v43, v0
	v_mov_b32_e32 v44, v0
	v_mov_b32_e32 v45, v0
	v_mov_b32_e32 v46, v0
	v_mov_b32_e32 v47, v0
	v_mov_b32_e32 v56, v0
	v_mov_b32_e32 v57, v0
	v_mov_b32_e32 v58, v0
	v_mov_b32_e32 v59, v0
	v_mov_b32_e32 v60, v0
	v_mov_b32_e32 v61, v0
	v_mov_b32_e32 v62, v0
	v_mov_b32_e32 v63, v0
	v_mov_b32_e32 v64, v0
	v_mov_b32_e32 v65, v0
	v_mov_b32_e32 v66, v0
	v_mov_b32_e32 v67, v0
	v_mov_b32_e32 v68, v0
	v_mov_b32_e32 v69, v0
	v_mov_b32_e32 v70, v0
	v_mov_b32_e32 v71, v0
	v_mov_b32_e32 v80, v0
	v_mov_b32_e32 v81, v0
	v_mov_b32_e32 v82, v0
	v_mov_b32_e32 v83, v0
	v_mov_b32_e32 v84, v0
	v_mov_b32_e32 v85, v0
	v_mov_b32_e32 v86, v0
	v_mov_b32_e32 v87, v0
	v_mov_b32_e32 v96, v0
	v_mov_b32_e32 v97, v0
	v_mov_b32_e32 v98, v0
	v_mov_b32_e32 v99, v0
	v_mov_b32_e32 v100, v0
	v_mov_b32_e32 v101, v0
	v_mov_b32_e32 v102, v0
	v_mov_b32_e32 v103, v0
	v_mov_b32_e32 v112, v0
	v_mov_b32_e32 v113, v0
	v_mov_b32_e32 v114, v0
	v_mov_b32_e32 v115, v0
	v_mov_b32_e32 v116, v0
	v_mov_b32_e32 v117, v0
	v_mov_b32_e32 v118, v0
	v_mov_b32_e32 v119, v0
	v_mov_b32_e32 v72, v0
	v_mov_b32_e32 v73, v0
	v_mov_b32_e32 v74, v0
	v_mov_b32_e32 v75, v0
	v_mov_b32_e32 v76, v0
	v_mov_b32_e32 v77, v0
	v_mov_b32_e32 v78, v0
	v_mov_b32_e32 v79, v0
	v_mov_b32_e32 v88, v0
	v_mov_b32_e32 v89, v0
	v_mov_b32_e32 v90, v0
	v_mov_b32_e32 v91, v0
	v_mov_b32_e32 v92, v0
	v_mov_b32_e32 v93, v0
	v_mov_b32_e32 v94, v0
	v_mov_b32_e32 v95, v0
	v_mov_b32_e32 v104, v0
	v_mov_b32_e32 v105, v0
	v_mov_b32_e32 v106, v0
	v_mov_b32_e32 v107, v0
	v_mov_b32_e32 v108, v0
	v_mov_b32_e32 v109, v0
	v_mov_b32_e32 v110, v0
	v_mov_b32_e32 v111, v0
	v_mov_b32_e32 v120, v0
	v_mov_b32_e32 v121, v0
	v_mov_b32_e32 v122, v0
	v_mov_b32_e32 v123, v0
	v_mov_b32_e32 v124, v0
	v_mov_b32_e32 v125, v0
	v_mov_b32_e32 v126, v0
	v_mov_b32_e32 v127, v0
	.p2alignl 6, 3212836864

.LBB0_672:
	s_ashr_i32 s25, s24, 31
	s_lshl_b64 s[26:27], s[24:25], 20
	s_add_u32 s26, s38, s26
	s_addc_u32 s27, s39, s27
	s_and_b64 s[28:29], s[6:7], exec
	s_cselect_b32 s25, s27, s31
	s_cselect_b32 s65, s26, s30
	s_ashr_i32 s23, s22, 31
	s_lshl_b64 s[28:29], s[22:23], 20
	s_add_u32 s28, s40, s28
	s_addc_u32 s29, s41, s29
	s_and_b64 s[36:37], s[6:7], exec
	s_cselect_b32 s23, s29, s35
	s_cselect_b32 s66, s28, s34
	s_add_u32 s30, s30, 0x80080
	s_addc_u32 s31, s31, 0
	s_add_u32 s67, s34, 0x100
	v_mov_b32_e32 v8, 0
	s_addc_u32 s68, s35, 0
	s_mov_b32 s69, -2
	v_mov_b32_e32 v9, v8
	v_mov_b32_e32 v10, v8
	v_mov_b32_e32 v11, v8
	v_mov_b32_e32 v12, v8
	v_mov_b32_e32 v13, v8
	v_mov_b32_e32 v14, v8
	v_mov_b32_e32 v15, v8
	v_mov_b32_e32 v24, v8
	v_mov_b32_e32 v25, v8
	v_mov_b32_e32 v26, v8
	v_mov_b32_e32 v27, v8
	v_mov_b32_e32 v28, v8
	v_mov_b32_e32 v29, v8
	v_mov_b32_e32 v30, v8
	v_mov_b32_e32 v31, v8
	v_mov_b32_e32 v40, v8
	v_mov_b32_e32 v41, v8
	v_mov_b32_e32 v42, v8
	v_mov_b32_e32 v43, v8
	v_mov_b32_e32 v44, v8
	v_mov_b32_e32 v45, v8
	v_mov_b32_e32 v46, v8
	v_mov_b32_e32 v47, v8
	v_mov_b32_e32 v56, v8
	v_mov_b32_e32 v57, v8
	v_mov_b32_e32 v58, v8
	v_mov_b32_e32 v59, v8
	v_mov_b32_e32 v60, v8
	v_mov_b32_e32 v61, v8
	v_mov_b32_e32 v62, v8
	v_mov_b32_e32 v63, v8
	v_mov_b32_e32 v0, v8
	v_mov_b32_e32 v1, v8
	v_mov_b32_e32 v2, v8
	v_mov_b32_e32 v3, v8
	v_mov_b32_e32 v4, v8
	v_mov_b32_e32 v5, v8
	v_mov_b32_e32 v6, v8
	v_mov_b32_e32 v7, v8
	v_mov_b32_e32 v16, v8
	v_mov_b32_e32 v17, v8
	v_mov_b32_e32 v18, v8
	v_mov_b32_e32 v19, v8
	v_mov_b32_e32 v20, v8
	v_mov_b32_e32 v21, v8
	v_mov_b32_e32 v22, v8
	v_mov_b32_e32 v23, v8
	v_mov_b32_e32 v32, v8
	v_mov_b32_e32 v33, v8
	v_mov_b32_e32 v34, v8
	v_mov_b32_e32 v35, v8
	v_mov_b32_e32 v36, v8
	v_mov_b32_e32 v37, v8
	v_mov_b32_e32 v38, v8
	v_mov_b32_e32 v39, v8
	v_mov_b32_e32 v48, v8
	v_mov_b32_e32 v49, v8
	v_mov_b32_e32 v50, v8
	v_mov_b32_e32 v51, v8
	v_mov_b32_e32 v52, v8
	v_mov_b32_e32 v53, v8
	v_mov_b32_e32 v54, v8
	v_mov_b32_e32 v55, v8
	v_mov_b32_e32 v72, v8
	v_mov_b32_e32 v73, v8
	v_mov_b32_e32 v74, v8
	v_mov_b32_e32 v75, v8
	v_mov_b32_e32 v76, v8
	v_mov_b32_e32 v77, v8
	v_mov_b32_e32 v78, v8
	v_mov_b32_e32 v79, v8
	v_mov_b32_e32 v88, v8
	v_mov_b32_e32 v89, v8
	v_mov_b32_e32 v90, v8
	v_mov_b32_e32 v91, v8
	v_mov_b32_e32 v92, v8
	v_mov_b32_e32 v93, v8
	v_mov_b32_e32 v94, v8
	v_mov_b32_e32 v95, v8
	v_mov_b32_e32 v104, v8
	v_mov_b32_e32 v105, v8
	v_mov_b32_e32 v106, v8
	v_mov_b32_e32 v107, v8
	v_mov_b32_e32 v108, v8
	v_mov_b32_e32 v109, v8
	v_mov_b32_e32 v110, v8
	v_mov_b32_e32 v111, v8
	v_mov_b32_e32 v120, v8
	v_mov_b32_e32 v121, v8
	v_mov_b32_e32 v122, v8
	v_mov_b32_e32 v123, v8
	v_mov_b32_e32 v124, v8
	v_mov_b32_e32 v125, v8
	v_mov_b32_e32 v126, v8
	v_mov_b32_e32 v127, v8
	v_mov_b32_e32 v64, v8
	v_mov_b32_e32 v65, v8
	v_mov_b32_e32 v66, v8
	v_mov_b32_e32 v67, v8
	v_mov_b32_e32 v68, v8
	v_mov_b32_e32 v69, v8
	v_mov_b32_e32 v70, v8
	v_mov_b32_e32 v71, v8
	v_mov_b32_e32 v80, v8
	v_mov_b32_e32 v81, v8
	v_mov_b32_e32 v82, v8
	v_mov_b32_e32 v83, v8
	v_mov_b32_e32 v84, v8
	v_mov_b32_e32 v85, v8
	v_mov_b32_e32 v86, v8
	v_mov_b32_e32 v87, v8
	v_mov_b32_e32 v96, v8
	v_mov_b32_e32 v97, v8
	v_mov_b32_e32 v98, v8
	v_mov_b32_e32 v99, v8
	v_mov_b32_e32 v100, v8
	v_mov_b32_e32 v101, v8
	v_mov_b32_e32 v102, v8
	v_mov_b32_e32 v103, v8
	v_mov_b32_e32 v112, v8
	v_mov_b32_e32 v113, v8
	v_mov_b32_e32 v114, v8
	v_mov_b32_e32 v115, v8
	v_mov_b32_e32 v116, v8
	v_mov_b32_e32 v117, v8
	v_mov_b32_e32 v118, v8
	v_mov_b32_e32 v119, v8
	.p2alignl 6, 3212836864

.LBB0_1186:
	s_add_u32 s66, s30, 0x100
	v_mov_b32_e32 v0, 0
	s_addc_u32 s67, s31, 0
	s_mov_b32 s68, -2
	s_waitcnt lgkmcnt(0)
	v_mov_b32_e32 v1, v0
	v_mov_b32_e32 v2, v0
	v_mov_b32_e32 v3, v0
	v_mov_b32_e32 v4, v0
	v_mov_b32_e32 v5, v0
	v_mov_b32_e32 v6, v0
	v_mov_b32_e32 v7, v0
	v_mov_b32_e32 v16, v0
	v_mov_b32_e32 v17, v0
	v_mov_b32_e32 v18, v0
	v_mov_b32_e32 v19, v0
	v_mov_b32_e32 v20, v0
	v_mov_b32_e32 v21, v0
	v_mov_b32_e32 v22, v0
	v_mov_b32_e32 v23, v0
	v_mov_b32_e32 v32, v0
	v_mov_b32_e32 v33, v0
	v_mov_b32_e32 v34, v0
	v_mov_b32_e32 v35, v0
	v_mov_b32_e32 v36, v0
	v_mov_b32_e32 v37, v0
	v_mov_b32_e32 v38, v0
	v_mov_b32_e32 v39, v0
	v_mov_b32_e32 v48, v0
	v_mov_b32_e32 v49, v0
	v_mov_b32_e32 v50, v0
	v_mov_b32_e32 v51, v0
	v_mov_b32_e32 v52, v0
	v_mov_b32_e32 v53, v0
	v_mov_b32_e32 v54, v0
	v_mov_b32_e32 v55, v0
	v_mov_b32_e32 v8, v0
	v_mov_b32_e32 v9, v0
	v_mov_b32_e32 v10, v0
	v_mov_b32_e32 v11, v0
	v_mov_b32_e32 v12, v0
	v_mov_b32_e32 v13, v0
	v_mov_b32_e32 v14, v0
	v_mov_b32_e32 v15, v0
	v_mov_b32_e32 v24, v0
	v_mov_b32_e32 v25, v0
	v_mov_b32_e32 v26, v0
	v_mov_b32_e32 v27, v0
	v_mov_b32_e32 v28, v0
	v_mov_b32_e32 v29, v0
	v_mov_b32_e32 v30, v0
	v_mov_b32_e32 v31, v0
	v_mov_b32_e32 v40, v0
	v_mov_b32_e32 v41, v0
	v_mov_b32_e32 v42, v0
	v_mov_b32_e32 v43, v0
	v_mov_b32_e32 v44, v0
	v_mov_b32_e32 v45, v0
	v_mov_b32_e32 v46, v0
	v_mov_b32_e32 v47, v0
	v_mov_b32_e32 v56, v0
	v_mov_b32_e32 v57, v0
	v_mov_b32_e32 v58, v0
	v_mov_b32_e32 v59, v0
	v_mov_b32_e32 v60, v0
	v_mov_b32_e32 v61, v0
	v_mov_b32_e32 v62, v0
	v_mov_b32_e32 v63, v0
	v_mov_b32_e32 v64, v0
	v_mov_b32_e32 v65, v0
	v_mov_b32_e32 v66, v0
	v_mov_b32_e32 v67, v0
	v_mov_b32_e32 v68, v0
	v_mov_b32_e32 v69, v0
	v_mov_b32_e32 v70, v0
	v_mov_b32_e32 v71, v0
	v_mov_b32_e32 v80, v0
	v_mov_b32_e32 v81, v0
	v_mov_b32_e32 v82, v0
	v_mov_b32_e32 v83, v0
	v_mov_b32_e32 v84, v0
	v_mov_b32_e32 v85, v0
	v_mov_b32_e32 v86, v0
	v_mov_b32_e32 v87, v0
	v_mov_b32_e32 v96, v0
	v_mov_b32_e32 v97, v0
	v_mov_b32_e32 v98, v0
	v_mov_b32_e32 v99, v0
	v_mov_b32_e32 v100, v0
	v_mov_b32_e32 v101, v0
	v_mov_b32_e32 v102, v0
	v_mov_b32_e32 v103, v0
	v_mov_b32_e32 v112, v0
	v_mov_b32_e32 v113, v0
	v_mov_b32_e32 v114, v0
	v_mov_b32_e32 v115, v0
	v_mov_b32_e32 v116, v0
	v_mov_b32_e32 v117, v0
	v_mov_b32_e32 v118, v0
	v_mov_b32_e32 v119, v0
	v_mov_b32_e32 v72, v0
	v_mov_b32_e32 v73, v0
	v_mov_b32_e32 v74, v0
	v_mov_b32_e32 v75, v0
	v_mov_b32_e32 v76, v0
	v_mov_b32_e32 v77, v0
	v_mov_b32_e32 v78, v0
	v_mov_b32_e32 v79, v0
	v_mov_b32_e32 v88, v0
	v_mov_b32_e32 v89, v0
	v_mov_b32_e32 v90, v0
	v_mov_b32_e32 v91, v0
	v_mov_b32_e32 v92, v0
	v_mov_b32_e32 v93, v0
	v_mov_b32_e32 v94, v0
	v_mov_b32_e32 v95, v0
	v_mov_b32_e32 v104, v0
	v_mov_b32_e32 v105, v0
	v_mov_b32_e32 v106, v0
	v_mov_b32_e32 v107, v0
	v_mov_b32_e32 v108, v0
	v_mov_b32_e32 v109, v0
	v_mov_b32_e32 v110, v0
	v_mov_b32_e32 v111, v0
	v_mov_b32_e32 v120, v0
	v_mov_b32_e32 v121, v0
	v_mov_b32_e32 v122, v0
	v_mov_b32_e32 v123, v0
	v_mov_b32_e32 v124, v0
	v_mov_b32_e32 v125, v0
	v_mov_b32_e32 v126, v0
	v_mov_b32_e32 v127, v0
	.p2alignl 6, 3212836864

.LBB0_1270:
	s_ashr_i32 s25, s24, 31
	s_lshl_b64 s[26:27], s[24:25], 20
	s_add_u32 s26, s38, s26
	s_addc_u32 s27, s39, s27
	s_and_b64 s[28:29], s[6:7], exec
	s_cselect_b32 s25, s27, s31
	s_cselect_b32 s63, s26, s30
	s_ashr_i32 s23, s22, 31
	s_lshl_b64 s[28:29], s[22:23], 20
	s_add_u32 s28, s40, s28
	s_addc_u32 s29, s41, s29
	s_and_b64 s[36:37], s[6:7], exec
	s_cselect_b32 s23, s29, s35
	s_cselect_b32 s64, s28, s34
	s_add_u32 s30, s30, 0x80080
	s_addc_u32 s31, s31, 0
	s_add_u32 s65, s34, 0x100
	v_mov_b32_e32 v0, 0
	s_addc_u32 s66, s35, 0
	s_mov_b32 s67, -2
	v_mov_b32_e32 v1, v0
	v_mov_b32_e32 v2, v0
	v_mov_b32_e32 v3, v0
	v_mov_b32_e32 v4, v0
	v_mov_b32_e32 v5, v0
	v_mov_b32_e32 v6, v0
	v_mov_b32_e32 v7, v0
	v_mov_b32_e32 v16, v0
	v_mov_b32_e32 v17, v0
	v_mov_b32_e32 v18, v0
	v_mov_b32_e32 v19, v0
	v_mov_b32_e32 v20, v0
	v_mov_b32_e32 v21, v0
	v_mov_b32_e32 v22, v0
	v_mov_b32_e32 v23, v0
	v_mov_b32_e32 v32, v0
	v_mov_b32_e32 v33, v0
	v_mov_b32_e32 v34, v0
	v_mov_b32_e32 v35, v0
	v_mov_b32_e32 v36, v0
	v_mov_b32_e32 v37, v0
	v_mov_b32_e32 v38, v0
	v_mov_b32_e32 v39, v0
	v_mov_b32_e32 v48, v0
	v_mov_b32_e32 v49, v0
	v_mov_b32_e32 v50, v0
	v_mov_b32_e32 v51, v0
	v_mov_b32_e32 v52, v0
	v_mov_b32_e32 v53, v0
	v_mov_b32_e32 v54, v0
	v_mov_b32_e32 v55, v0
	v_mov_b32_e32 v8, v0
	v_mov_b32_e32 v9, v0
	v_mov_b32_e32 v10, v0
	v_mov_b32_e32 v11, v0
	v_mov_b32_e32 v12, v0
	v_mov_b32_e32 v13, v0
	v_mov_b32_e32 v14, v0
	v_mov_b32_e32 v15, v0
	v_mov_b32_e32 v24, v0
	v_mov_b32_e32 v25, v0
	v_mov_b32_e32 v26, v0
	v_mov_b32_e32 v27, v0
	v_mov_b32_e32 v28, v0
	v_mov_b32_e32 v29, v0
	v_mov_b32_e32 v30, v0
	v_mov_b32_e32 v31, v0
	v_mov_b32_e32 v40, v0
	v_mov_b32_e32 v41, v0
	v_mov_b32_e32 v42, v0
	v_mov_b32_e32 v43, v0
	v_mov_b32_e32 v44, v0
	v_mov_b32_e32 v45, v0
	v_mov_b32_e32 v46, v0
	v_mov_b32_e32 v47, v0
	v_mov_b32_e32 v56, v0
	v_mov_b32_e32 v57, v0
	v_mov_b32_e32 v58, v0
	v_mov_b32_e32 v59, v0
	v_mov_b32_e32 v60, v0
	v_mov_b32_e32 v61, v0
	v_mov_b32_e32 v62, v0
	v_mov_b32_e32 v63, v0
	v_mov_b32_e32 v64, v0
	v_mov_b32_e32 v65, v0
	v_mov_b32_e32 v66, v0
	v_mov_b32_e32 v67, v0
	v_mov_b32_e32 v68, v0
	v_mov_b32_e32 v69, v0
	v_mov_b32_e32 v70, v0
	v_mov_b32_e32 v71, v0
	v_mov_b32_e32 v80, v0
	v_mov_b32_e32 v81, v0
	v_mov_b32_e32 v82, v0
	v_mov_b32_e32 v83, v0
	v_mov_b32_e32 v84, v0
	v_mov_b32_e32 v85, v0
	v_mov_b32_e32 v86, v0
	v_mov_b32_e32 v87, v0
	v_mov_b32_e32 v96, v0
	v_mov_b32_e32 v97, v0
	v_mov_b32_e32 v98, v0
	v_mov_b32_e32 v99, v0
	v_mov_b32_e32 v100, v0
	v_mov_b32_e32 v101, v0
	v_mov_b32_e32 v102, v0
	v_mov_b32_e32 v103, v0
	v_mov_b32_e32 v112, v0
	v_mov_b32_e32 v113, v0
	v_mov_b32_e32 v114, v0
	v_mov_b32_e32 v115, v0
	v_mov_b32_e32 v116, v0
	v_mov_b32_e32 v117, v0
	v_mov_b32_e32 v118, v0
	v_mov_b32_e32 v119, v0
	v_mov_b32_e32 v72, v0
	v_mov_b32_e32 v73, v0
	v_mov_b32_e32 v74, v0
	v_mov_b32_e32 v75, v0
	v_mov_b32_e32 v76, v0
	v_mov_b32_e32 v77, v0
	v_mov_b32_e32 v78, v0
	v_mov_b32_e32 v79, v0
	v_mov_b32_e32 v88, v0
	v_mov_b32_e32 v89, v0
	v_mov_b32_e32 v90, v0
	v_mov_b32_e32 v91, v0
	v_mov_b32_e32 v92, v0
	v_mov_b32_e32 v93, v0
	v_mov_b32_e32 v94, v0
	v_mov_b32_e32 v95, v0
	v_mov_b32_e32 v104, v0
	v_mov_b32_e32 v105, v0
	v_mov_b32_e32 v106, v0
	v_mov_b32_e32 v107, v0
	v_mov_b32_e32 v108, v0
	v_mov_b32_e32 v109, v0
	v_mov_b32_e32 v110, v0
	v_mov_b32_e32 v111, v0
	v_mov_b32_e32 v120, v0
	v_mov_b32_e32 v121, v0
	v_mov_b32_e32 v122, v0
	v_mov_b32_e32 v123, v0
	v_mov_b32_e32 v124, v0
	v_mov_b32_e32 v125, v0
	v_mov_b32_e32 v126, v0
	v_mov_b32_e32 v127, v0
	.p2alignl 6, 3212836864

.LBB0_1334:
	s_and_b64 vcc, exec, s[10:11]
	s_cbranch_vccnz .LBB0_1332
	.p2alignl 6, 3212836864

.LBB0_1419:
	s_ashr_i32 s27, s26, 31
	s_lshl_b64 s[28:29], s[26:27], 20
	s_add_u32 s28, s48, s28
	s_addc_u32 s29, s49, s29
	s_and_b64 s[30:31], s[8:9], exec
	s_cselect_b32 s27, s29, s39
	s_cselect_b32 s35, s28, s38
	s_ashr_i32 s25, s24, 31
	s_lshl_b64 s[30:31], s[24:25], 20
	s_add_u32 s30, s50, s30
	s_addc_u32 s31, s51, s31
	s_and_b64 s[42:43], s[8:9], exec
	s_cselect_b32 s25, s31, s41
	s_cselect_b32 s65, s30, s40
	s_add_u32 s38, s38, 0x80080
	s_addc_u32 s39, s39, 0
	s_add_u32 s66, s40, 0x100
	v_mov_b32_e32 v0, 0
	s_addc_u32 s67, s41, 0
	s_mov_b32 s68, -2
	s_waitcnt lgkmcnt(0)
	v_mov_b32_e32 v1, v0
	v_mov_b32_e32 v2, v0
	v_mov_b32_e32 v3, v0
	v_mov_b32_e32 v4, v0
	v_mov_b32_e32 v5, v0
	v_mov_b32_e32 v6, v0
	v_mov_b32_e32 v7, v0
	v_mov_b32_e32 v16, v0
	v_mov_b32_e32 v17, v0
	v_mov_b32_e32 v18, v0
	v_mov_b32_e32 v19, v0
	v_mov_b32_e32 v20, v0
	v_mov_b32_e32 v21, v0
	v_mov_b32_e32 v22, v0
	v_mov_b32_e32 v23, v0
	v_mov_b32_e32 v32, v0
	v_mov_b32_e32 v33, v0
	v_mov_b32_e32 v34, v0
	v_mov_b32_e32 v35, v0
	v_mov_b32_e32 v36, v0
	v_mov_b32_e32 v37, v0
	v_mov_b32_e32 v38, v0
	v_mov_b32_e32 v39, v0
	v_mov_b32_e32 v48, v0
	v_mov_b32_e32 v49, v0
	v_mov_b32_e32 v50, v0
	v_mov_b32_e32 v51, v0
	v_mov_b32_e32 v52, v0
	v_mov_b32_e32 v53, v0
	v_mov_b32_e32 v54, v0
	v_mov_b32_e32 v55, v0
	v_mov_b32_e32 v8, v0
	v_mov_b32_e32 v9, v0
	v_mov_b32_e32 v10, v0
	v_mov_b32_e32 v11, v0
	v_mov_b32_e32 v12, v0
	v_mov_b32_e32 v13, v0
	v_mov_b32_e32 v14, v0
	v_mov_b32_e32 v15, v0
	v_mov_b32_e32 v24, v0
	v_mov_b32_e32 v25, v0
	v_mov_b32_e32 v26, v0
	v_mov_b32_e32 v27, v0
	v_mov_b32_e32 v28, v0
	v_mov_b32_e32 v29, v0
	v_mov_b32_e32 v30, v0
	v_mov_b32_e32 v31, v0
	v_mov_b32_e32 v40, v0
	v_mov_b32_e32 v41, v0
	v_mov_b32_e32 v42, v0
	v_mov_b32_e32 v43, v0
	v_mov_b32_e32 v44, v0
	v_mov_b32_e32 v45, v0
	v_mov_b32_e32 v46, v0
	v_mov_b32_e32 v47, v0
	v_mov_b32_e32 v56, v0
	v_mov_b32_e32 v57, v0
	v_mov_b32_e32 v58, v0
	v_mov_b32_e32 v59, v0
	v_mov_b32_e32 v60, v0
	v_mov_b32_e32 v61, v0
	v_mov_b32_e32 v62, v0
	v_mov_b32_e32 v63, v0
	v_mov_b32_e32 v64, v0
	v_mov_b32_e32 v65, v0
	v_mov_b32_e32 v66, v0
	v_mov_b32_e32 v67, v0
	v_mov_b32_e32 v68, v0
	v_mov_b32_e32 v69, v0
	v_mov_b32_e32 v70, v0
	v_mov_b32_e32 v71, v0
	v_mov_b32_e32 v80, v0
	v_mov_b32_e32 v81, v0
	v_mov_b32_e32 v82, v0
	v_mov_b32_e32 v83, v0
	v_mov_b32_e32 v84, v0
	v_mov_b32_e32 v85, v0
	v_mov_b32_e32 v86, v0
	v_mov_b32_e32 v87, v0
	v_mov_b32_e32 v96, v0
	v_mov_b32_e32 v97, v0
	v_mov_b32_e32 v98, v0
	v_mov_b32_e32 v99, v0
	v_mov_b32_e32 v100, v0
	v_mov_b32_e32 v101, v0
	v_mov_b32_e32 v102, v0
	v_mov_b32_e32 v103, v0
	v_mov_b32_e32 v112, v0
	v_mov_b32_e32 v113, v0
	v_mov_b32_e32 v114, v0
	v_mov_b32_e32 v115, v0
	v_mov_b32_e32 v116, v0
	v_mov_b32_e32 v117, v0
	v_mov_b32_e32 v118, v0
	v_mov_b32_e32 v119, v0
	v_mov_b32_e32 v72, v0
	v_mov_b32_e32 v73, v0
	v_mov_b32_e32 v74, v0
	v_mov_b32_e32 v75, v0
	v_mov_b32_e32 v76, v0
	v_mov_b32_e32 v77, v0
	v_mov_b32_e32 v78, v0
	v_mov_b32_e32 v79, v0
	v_mov_b32_e32 v88, v0
	v_mov_b32_e32 v89, v0
	v_mov_b32_e32 v90, v0
	v_mov_b32_e32 v91, v0
	v_mov_b32_e32 v92, v0
	v_mov_b32_e32 v93, v0
	v_mov_b32_e32 v94, v0
	v_mov_b32_e32 v95, v0
	v_mov_b32_e32 v104, v0
	v_mov_b32_e32 v105, v0
	v_mov_b32_e32 v106, v0
	v_mov_b32_e32 v107, v0
	v_mov_b32_e32 v108, v0
	v_mov_b32_e32 v109, v0
	v_mov_b32_e32 v110, v0
	v_mov_b32_e32 v111, v0
	v_mov_b32_e32 v120, v0
	v_mov_b32_e32 v121, v0
	v_mov_b32_e32 v122, v0
	v_mov_b32_e32 v123, v0
	v_mov_b32_e32 v124, v0
	v_mov_b32_e32 v125, v0
	v_mov_b32_e32 v126, v0
	v_mov_b32_e32 v127, v0
	.p2alignl 6, 3212836864

.LBB0_1503:
	s_ashr_i32 s23, s22, 31
	s_lshl_b64 s[24:25], s[22:23], 20
	s_add_u32 s24, s36, s24
	s_addc_u32 s25, s37, s25
	s_and_b64 s[26:27], s[6:7], exec
	s_cselect_b32 s23, s25, s29
	s_cselect_b32 s61, s24, s28
	s_ashr_i32 s21, s20, 31
	s_lshl_b64 s[26:27], s[20:21], 20
	s_add_u32 s26, s38, s26
	s_addc_u32 s27, s39, s27
	s_and_b64 s[34:35], s[6:7], exec
	s_cselect_b32 s21, s27, s31
	s_cselect_b32 s62, s26, s30
	s_add_u32 s28, s28, 0x80080
	s_addc_u32 s29, s29, 0
	s_add_u32 s63, s30, 0x100
	v_mov_b32_e32 v8, 0
	s_addc_u32 s64, s31, 0
	s_mov_b32 s65, -2
	v_mov_b32_e32 v9, v8
	v_mov_b32_e32 v10, v8
	v_mov_b32_e32 v11, v8
	v_mov_b32_e32 v12, v8
	v_mov_b32_e32 v13, v8
	v_mov_b32_e32 v14, v8
	v_mov_b32_e32 v15, v8
	v_mov_b32_e32 v24, v8
	v_mov_b32_e32 v25, v8
	v_mov_b32_e32 v26, v8
	v_mov_b32_e32 v27, v8
	v_mov_b32_e32 v28, v8
	v_mov_b32_e32 v29, v8
	v_mov_b32_e32 v30, v8
	v_mov_b32_e32 v31, v8
	v_mov_b32_e32 v40, v8
	v_mov_b32_e32 v41, v8
	v_mov_b32_e32 v42, v8
	v_mov_b32_e32 v43, v8
	v_mov_b32_e32 v44, v8
	v_mov_b32_e32 v45, v8
	v_mov_b32_e32 v46, v8
	v_mov_b32_e32 v47, v8
	v_mov_b32_e32 v56, v8
	v_mov_b32_e32 v57, v8
	v_mov_b32_e32 v58, v8
	v_mov_b32_e32 v59, v8
	v_mov_b32_e32 v60, v8
	v_mov_b32_e32 v61, v8
	v_mov_b32_e32 v62, v8
	v_mov_b32_e32 v63, v8
	v_mov_b32_e32 v0, v8
	v_mov_b32_e32 v1, v8
	v_mov_b32_e32 v2, v8
	v_mov_b32_e32 v3, v8
	v_mov_b32_e32 v4, v8
	v_mov_b32_e32 v5, v8
	v_mov_b32_e32 v6, v8
	v_mov_b32_e32 v7, v8
	v_mov_b32_e32 v16, v8
	v_mov_b32_e32 v17, v8
	v_mov_b32_e32 v18, v8
	v_mov_b32_e32 v19, v8
	v_mov_b32_e32 v20, v8
	v_mov_b32_e32 v21, v8
	v_mov_b32_e32 v22, v8
	v_mov_b32_e32 v23, v8
	v_mov_b32_e32 v32, v8
	v_mov_b32_e32 v33, v8
	v_mov_b32_e32 v34, v8
	v_mov_b32_e32 v35, v8
	v_mov_b32_e32 v36, v8
	v_mov_b32_e32 v37, v8
	v_mov_b32_e32 v38, v8
	v_mov_b32_e32 v39, v8
	v_mov_b32_e32 v48, v8
	v_mov_b32_e32 v49, v8
	v_mov_b32_e32 v50, v8
	v_mov_b32_e32 v51, v8
	v_mov_b32_e32 v52, v8
	v_mov_b32_e32 v53, v8
	v_mov_b32_e32 v54, v8
	v_mov_b32_e32 v55, v8
	v_mov_b32_e32 v72, v8
	v_mov_b32_e32 v73, v8
	v_mov_b32_e32 v74, v8
	v_mov_b32_e32 v75, v8
	v_mov_b32_e32 v76, v8
	v_mov_b32_e32 v77, v8
	v_mov_b32_e32 v78, v8
	v_mov_b32_e32 v79, v8
	v_mov_b32_e32 v88, v8
	v_mov_b32_e32 v89, v8
	v_mov_b32_e32 v90, v8
	v_mov_b32_e32 v91, v8
	v_mov_b32_e32 v92, v8
	v_mov_b32_e32 v93, v8
	v_mov_b32_e32 v94, v8
	v_mov_b32_e32 v95, v8
	v_mov_b32_e32 v104, v8
	v_mov_b32_e32 v105, v8
	v_mov_b32_e32 v106, v8
	v_mov_b32_e32 v107, v8
	v_mov_b32_e32 v108, v8
	v_mov_b32_e32 v109, v8
	v_mov_b32_e32 v110, v8
	v_mov_b32_e32 v111, v8
	v_mov_b32_e32 v120, v8
	v_mov_b32_e32 v121, v8
	v_mov_b32_e32 v122, v8
	v_mov_b32_e32 v123, v8
	v_mov_b32_e32 v124, v8
	v_mov_b32_e32 v125, v8
	v_mov_b32_e32 v126, v8
	v_mov_b32_e32 v127, v8
	v_mov_b32_e32 v64, v8
	v_mov_b32_e32 v65, v8
	v_mov_b32_e32 v66, v8
	v_mov_b32_e32 v67, v8
	v_mov_b32_e32 v68, v8
	v_mov_b32_e32 v69, v8
	v_mov_b32_e32 v70, v8
	v_mov_b32_e32 v71, v8
	v_mov_b32_e32 v80, v8
	v_mov_b32_e32 v81, v8
	v_mov_b32_e32 v82, v8
	v_mov_b32_e32 v83, v8
	v_mov_b32_e32 v84, v8
	v_mov_b32_e32 v85, v8
	v_mov_b32_e32 v86, v8
	v_mov_b32_e32 v87, v8
	v_mov_b32_e32 v96, v8
	v_mov_b32_e32 v97, v8
	v_mov_b32_e32 v98, v8
	v_mov_b32_e32 v99, v8
	v_mov_b32_e32 v100, v8
	v_mov_b32_e32 v101, v8
	v_mov_b32_e32 v102, v8
	v_mov_b32_e32 v103, v8
	v_mov_b32_e32 v112, v8
	v_mov_b32_e32 v113, v8
	v_mov_b32_e32 v114, v8
	v_mov_b32_e32 v115, v8
	v_mov_b32_e32 v116, v8
	v_mov_b32_e32 v117, v8
	v_mov_b32_e32 v118, v8
	v_mov_b32_e32 v119, v8
	.p2alignl 6, 3212836864

.LBB0_2112:
	s_add_u32 s21, s26, 0x100
	s_addc_u32 s53, s27, 0
	v_lshl_add_u64 v[144:145], s[24:25], 0, v[136:137]
	v_lshl_add_u64 v[146:147], s[24:25], 0, v[138:139]
	s_mov_b32 s54, -2
	s_mov_b64 s[26:27], 0
	.p2alignl 6, 3212836864
